# attention main loop: a third P.V MFMA of each step moved into the row-max section (wait lgkmcnt(10)); on top of all40
# baseline (speedup 1.0000x reference)
.LBB0_1547:
	v_add_u32_e32 v0, s8, v221
	ds_read_b64_tr_b16 v[192:193], v0 offset:24576
	ds_read_b64_tr_b16 v[194:195], v0 offset:25088
	s_waitcnt lgkmcnt(9)
	v_mfma_f32_32x32x16_bf16 v[112:127], v[188:191], v[148:151], v[48:63]
	v_add_f32_e32 v2, v80, v81
	v_add_f32_e32 v2, v82, v2
	v_add_f32_e32 v2, v83, v2
	v_add_f32_e32 v2, v84, v2
	v_add_f32_e32 v2, v85, v2
	v_cvt_pk_bf16_f32 v156, v80, v81
	v_cvt_pk_bf16_f32 v157, v82, v83
	ds_read_b64_tr_b16 v[188:189], v0 offset:28672
	ds_read_b64_tr_b16 v[190:191], v0 offset:29184
	s_waitcnt lgkmcnt(10)
	v_mfma_f32_32x32x16_bf16 v[96:111], v[184:187], v[148:151], v[48:63]
	v_add_f32_e32 v2, v86, v2
	v_add_f32_e32 v2, v87, v2
	v_add_f32_e32 v2, v88, v2
	v_add_f32_e32 v2, v89, v2
	v_cvt_pk_bf16_f32 v158, v84, v85
	v_cvt_pk_bf16_f32 v159, v86, v87
	ds_read_b64_tr_b16 v[184:185], v0 offset:25600
	ds_read_b64_tr_b16 v[186:187], v0 offset:26112
	s_waitcnt lgkmcnt(11)
	v_mfma_f32_32x32x16_bf16 v[112:127], v[180:183], v[140:143], v[112:127]
	v_add_f32_e32 v2, v90, v2
	v_add_f32_e32 v2, v91, v2
	v_add_f32_e32 v2, v92, v2
	v_add_f32_e32 v2, v93, v2
	v_cvt_pk_bf16_f32 v152, v88, v89
	v_cvt_pk_bf16_f32 v153, v90, v91
	ds_read_b64_tr_b16 v[84:85], v0 offset:29696
	ds_read_b64_tr_b16 v[86:87], v0 offset:30208
	s_waitcnt lgkmcnt(12)
	v_mfma_f32_32x32x16_bf16 v[96:111], v[176:179], v[140:143], v[96:111]
	v_add_f32_e32 v2, v94, v2
	v_add_f32_e32 v2, v95, v2
	v_add_f32_e32 v2, v64, v2
	v_add_f32_e32 v2, v65, v2
	v_cvt_pk_bf16_f32 v154, v92, v93
	v_cvt_pk_bf16_f32 v155, v94, v95
	ds_read_b64_tr_b16 v[80:81], v0 offset:26624
	ds_read_b64_tr_b16 v[82:83], v0 offset:27136
	s_waitcnt lgkmcnt(13)
	v_mfma_f32_32x32x16_bf16 v[112:127], v[172:175], v[132:135], v[112:127]
	v_add_f32_e32 v2, v66, v2
	v_add_f32_e32 v2, v67, v2
	v_add_f32_e32 v2, v68, v2
	v_add_f32_e32 v2, v69, v2
	v_cvt_pk_bf16_f32 v144, v64, v65
	v_cvt_pk_bf16_f32 v145, v66, v67
	ds_read_b64_tr_b16 v[10:11], v0 offset:30720
	ds_read_b64_tr_b16 v[12:13], v0 offset:31232
	s_waitcnt lgkmcnt(14)
	v_mfma_f32_32x32x16_bf16 v[96:111], v[168:171], v[132:135], v[96:111]
	v_add_f32_e32 v2, v70, v2
	v_add_f32_e32 v2, v71, v2
	v_add_f32_e32 v2, v72, v2
	v_add_f32_e32 v2, v73, v2
	v_cvt_pk_bf16_f32 v146, v68, v69
	v_cvt_pk_bf16_f32 v147, v70, v71
	ds_read_b64_tr_b16 v[6:7], v0 offset:27648
	ds_read_b64_tr_b16 v[8:9], v0 offset:28160
	s_waitcnt lgkmcnt(14)
	v_mfma_f32_32x32x16_bf16 v[112:127], v[164:167], v[128:131], v[112:127]
	v_add_f32_e32 v2, v74, v2
	v_add_f32_e32 v2, v75, v2
	v_add_f32_e32 v2, v76, v2
	v_add_f32_e32 v14, v77, v2
	v_cvt_pk_bf16_f32 v136, v72, v73
	v_cvt_pk_bf16_f32 v137, v74, v75
	ds_read_b64_tr_b16 v[2:3], v0 offset:31744
	ds_read_b64_tr_b16 v[4:5], v0 offset:32256
	v_mfma_f32_32x32x16_bf16 v[96:111], v[160:163], v[128:131], v[96:111]
	v_add_f32_e32 v0, v78, v14
	v_add_f32_e32 v0, v79, v0
	v_cvt_pk_bf16_f32 v138, v76, v77
	v_cvt_pk_bf16_f32 v139, v78, v79
	v_lshl_add_u64 v[14:15], v[202:203], 0, s[26:27]
	s_add_i32 s8, s40, s46
	s_mov_b32 s9, m0
	s_mov_b32 m0, s8
	s_nop 0
	global_load_lds_dwordx4 v[14:15], off
	s_mov_b32 m0, s9
	v_lshl_add_u64 v[14:15], v[200:201], 0, s[26:27]
	s_add_i32 s8, s38, s47
	s_mov_b32 s9, m0
	s_mov_b32 m0, s8
	s_nop 0
	global_load_lds_dwordx4 v[14:15], off
	s_mov_b32 m0, s9
	s_waitcnt lgkmcnt(14)
	v_mfma_f32_32x32x16_bf16 v[32:47], v[156:159], v[192:195], v[32:47]
	v_max_f32_e32 v14, v112, v113
	v_max3_f32 v15, v114, v115, v97
	v_max3_f32 v14, v14, v96, v98
	v_max3_f32 v14, v14, v99, v116
	v_max3_f32 v15, v15, v118, v119
	v_max3_f32 v14, v14, v117, v100
	s_waitcnt lgkmcnt(12)
	v_mfma_f32_32x32x16_bf16 v[16:31], v[156:159], v[188:191], v[16:31]
	v_max3_f32 v15, v15, v102, v103
	v_max3_f32 v14, v14, v101, v120
	v_max3_f32 v15, v15, v122, v123
	v_max3_f32 v14, v14, v121, v104
	v_max3_f32 v15, v15, v106, v107
	v_max3_f32 v14, v14, v105, v124
	v_max3_f32 v15, v15, v126, v127
	s_waitcnt lgkmcnt(10)
	v_mfma_f32_32x32x16_bf16 v[32:47], v[152:155], v[184:187], v[32:47]
	v_max3_f32 v64, v14, v125, v108
	v_max3_f32 v15, v15, v110, v111
	v_add_f32_e32 v14, v223, v0
	v_max3_f32 v0, v64, v109, v15
	v_mov_b32_e32 v15, v0
	s_nop 1
	v_permlane32_swap_b32_e32 v0, v15
	v_max_f32_e32 v0, v0, v15
	v_cmp_lt_f32_e32 vcc, s53, v0
	s_cmp_lg_u64 vcc, 0
	s_cselect_b64 s[8:9], -1, 0
	s_cbranch_vccnz .LBB0_1555
.LBB0_1548:
	v_exp_f32_e32 v112, v112
	v_exp_f32_e32 v113, v113
	v_exp_f32_e32 v114, v114
	v_exp_f32_e32 v115, v115
	v_exp_f32_e32 v116, v116
	v_exp_f32_e32 v117, v117
	v_exp_f32_e32 v118, v118
	v_exp_f32_e32 v119, v119
	v_add_u32_e32 v0, s38, v220
	ds_read_b128 v[64:67], v0
	ds_read_b128 v[160:163], v0 offset:512
	v_exp_f32_e32 v120, v120
	v_exp_f32_e32 v121, v121
	v_exp_f32_e32 v122, v122
	v_exp_f32_e32 v123, v123
	ds_read_b128 v[192:195], v0 offset:2048
	ds_read_b128 v[184:187], v0 offset:2560
	s_waitcnt lgkmcnt(12)
	v_mfma_f32_32x32x16_bf16 v[16:31], v[152:155], v[84:87], v[16:31]
	v_exp_f32_e32 v124, v124
	v_exp_f32_e32 v125, v125
	v_exp_f32_e32 v126, v126
	v_exp_f32_e32 v127, v127
	ds_read_b128 v[188:191], v0 offset:4096
	ds_read_b128 v[176:179], v0 offset:4608
	s_waitcnt lgkmcnt(12)
	v_mfma_f32_32x32x16_bf16 v[32:47], v[144:147], v[80:83], v[32:47]
	v_exp_f32_e32 v96, v96
	v_exp_f32_e32 v97, v97
	v_exp_f32_e32 v98, v98
	v_exp_f32_e32 v99, v99
	ds_read_b128 v[180:183], v0 offset:6144
	ds_read_b128 v[172:175], v0 offset:6656
	s_waitcnt lgkmcnt(12)
	v_mfma_f32_32x32x16_bf16 v[16:31], v[144:147], v[10:13], v[16:31]
	v_exp_f32_e32 v100, v100
	v_exp_f32_e32 v101, v101
	v_exp_f32_e32 v102, v102
	v_exp_f32_e32 v103, v103
	s_waitcnt lgkmcnt(10)
	v_mfma_f32_32x32x16_bf16 v[32:47], v[136:139], v[6:9], v[32:47]
	v_exp_f32_e32 v104, v104
	v_exp_f32_e32 v105, v105
	v_exp_f32_e32 v106, v106
	v_exp_f32_e32 v107, v107
	s_waitcnt lgkmcnt(8)
	v_mfma_f32_32x32x16_bf16 v[16:31], v[136:139], v[2:5], v[16:31]
	v_exp_f32_e32 v108, v108
	v_exp_f32_e32 v109, v109
	v_exp_f32_e32 v110, v110
	v_exp_f32_e32 v111, v111
	s_waitcnt vmcnt(2) lgkmcnt(0)
	s_barrier
	s_andn2_b64 vcc, exec, s[8:9]
	v_add_u32_e32 v0, s48, v222
	s_cbranch_vccnz .LBB0_1550
	s_waitcnt lgkmcnt(0)
	ds_read_b128 v[2:5], v0 offset:49248
	ds_read_b128 v[6:9], v0 offset:49216
	ds_read_b128 v[10:13], v0 offset:49184
	ds_read_b128 v[68:71], v0 offset:49152
	s_waitcnt lgkmcnt(3)
	v_pk_mul_f32 v[44:45], v[44:45], v[2:3]
	s_waitcnt lgkmcnt(2)
	v_pk_mul_f32 v[40:41], v[40:41], v[6:7]
	s_waitcnt lgkmcnt(1)
	v_pk_mul_f32 v[36:37], v[36:37], v[10:11]
	v_pk_mul_f32 v[46:47], v[46:47], v[4:5]
	v_pk_mul_f32 v[42:43], v[42:43], v[8:9]
	v_pk_mul_f32 v[38:39], v[38:39], v[12:13]
	s_waitcnt lgkmcnt(0)
	v_pk_mul_f32 v[34:35], v[34:35], v[70:71]
	v_pk_mul_f32 v[32:33], v[32:33], v[68:69]
	v_pk_mul_f32 v[28:29], v[28:29], v[2:3]
	v_pk_mul_f32 v[24:25], v[24:25], v[6:7]
	v_pk_mul_f32 v[20:21], v[20:21], v[10:11]
	v_pk_mul_f32 v[30:31], v[30:31], v[4:5]
	v_pk_mul_f32 v[26:27], v[26:27], v[8:9]
	v_pk_mul_f32 v[22:23], v[22:23], v[12:13]
	v_pk_mul_f32 v[18:19], v[18:19], v[70:71]
	v_pk_mul_f32 v[16:17], v[16:17], v[68:69]
.LBB0_1550:
	s_add_i32 s8, s38, 0x2000
	s_cmpk_lg_i32 s38, 0x4000
	s_cselect_b32 s13, s8, 0
	v_add_u32_e32 v4, s40, v221
	ds_read_b64_tr_b16 v[168:169], v4 offset:24576
	ds_read_b64_tr_b16 v[170:171], v4 offset:25088
	s_waitcnt lgkmcnt(9)
	v_mfma_f32_32x32x16_bf16 v[80:95], v[64:67], v[148:151], v[48:63]
	v_add_f32_e32 v2, v112, v113
	v_add_f32_e32 v2, v114, v2
	v_add_f32_e32 v2, v115, v2
	v_add_f32_e32 v2, v116, v2
	v_add_f32_e32 v2, v117, v2
	v_cvt_pk_bf16_f32 v156, v112, v113
	v_cvt_pk_bf16_f32 v157, v114, v115
	ds_read_b64_tr_b16 v[164:165], v4 offset:28672
	ds_read_b64_tr_b16 v[166:167], v4 offset:29184
	s_waitcnt lgkmcnt(10)
	v_mfma_f32_32x32x16_bf16 v[64:79], v[160:163], v[148:151], v[48:63]
	v_add_f32_e32 v2, v118, v2
	v_add_f32_e32 v2, v119, v2
	v_add_f32_e32 v2, v120, v2
	v_add_f32_e32 v2, v121, v2
	v_cvt_pk_bf16_f32 v158, v116, v117
	v_cvt_pk_bf16_f32 v159, v118, v119
	ds_read_b64_tr_b16 v[160:161], v4 offset:25600
	ds_read_b64_tr_b16 v[162:163], v4 offset:26112
	s_waitcnt lgkmcnt(11)
	v_mfma_f32_32x32x16_bf16 v[80:95], v[192:195], v[140:143], v[80:95]
	v_add_f32_e32 v2, v122, v2
	v_add_f32_e32 v2, v123, v2
	v_add_f32_e32 v2, v124, v2
	v_add_f32_e32 v2, v125, v2
	v_cvt_pk_bf16_f32 v152, v120, v121
	v_cvt_pk_bf16_f32 v153, v122, v123
	ds_read_b64_tr_b16 v[116:117], v4 offset:29696
	ds_read_b64_tr_b16 v[118:119], v4 offset:30208
	s_waitcnt lgkmcnt(12)
	v_mfma_f32_32x32x16_bf16 v[64:79], v[184:187], v[140:143], v[64:79]
	v_add_f32_e32 v2, v126, v2
	v_add_f32_e32 v2, v127, v2
	v_add_f32_e32 v2, v96, v2
	v_add_f32_e32 v2, v97, v2
	v_cvt_pk_bf16_f32 v154, v124, v125
	v_cvt_pk_bf16_f32 v155, v126, v127
	ds_read_b64_tr_b16 v[112:113], v4 offset:26624
	ds_read_b64_tr_b16 v[114:115], v4 offset:27136
	s_waitcnt lgkmcnt(13)
	v_mfma_f32_32x32x16_bf16 v[80:95], v[188:191], v[132:135], v[80:95]
	v_add_f32_e32 v2, v98, v2
	v_add_f32_e32 v2, v99, v2
	v_add_f32_e32 v2, v100, v2
	v_add_f32_e32 v2, v101, v2
	v_cvt_pk_bf16_f32 v144, v96, v97
	v_cvt_pk_bf16_f32 v145, v98, v99
	ds_read_b64_tr_b16 v[10:11], v4 offset:30720
	ds_read_b64_tr_b16 v[12:13], v4 offset:31232
	s_waitcnt lgkmcnt(14)
	v_mfma_f32_32x32x16_bf16 v[64:79], v[176:179], v[132:135], v[64:79]
	v_add_f32_e32 v2, v102, v2
	v_add_f32_e32 v2, v103, v2
	v_add_f32_e32 v2, v104, v2
	v_add_f32_e32 v2, v105, v2
	v_cvt_pk_bf16_f32 v146, v100, v101
	v_cvt_pk_bf16_f32 v147, v102, v103
	ds_read_b64_tr_b16 v[6:7], v4 offset:27648
	ds_read_b64_tr_b16 v[8:9], v4 offset:28160
	s_waitcnt lgkmcnt(14)
	v_mfma_f32_32x32x16_bf16 v[80:95], v[180:183], v[128:131], v[80:95]
	v_add_f32_e32 v2, v106, v2
	v_add_f32_e32 v2, v107, v2
	v_add_f32_e32 v2, v108, v2
	v_add_f32_e32 v15, v109, v2
	v_cvt_pk_bf16_f32 v136, v104, v105
	v_cvt_pk_bf16_f32 v137, v106, v107
	ds_read_b64_tr_b16 v[2:3], v4 offset:31744
	ds_read_b64_tr_b16 v[4:5], v4 offset:32256
	v_mfma_f32_32x32x16_bf16 v[64:79], v[172:175], v[128:131], v[64:79]
	v_add_f32_e32 v15, v110, v15
	v_add_f32_e32 v15, v111, v15
	v_add_f32_e32 v15, 0, v15
	v_cvt_pk_bf16_f32 v138, v108, v109
	v_cvt_pk_bf16_f32 v139, v110, v111
	s_waitcnt lgkmcnt(14)
	v_mfma_f32_32x32x16_bf16 v[32:47], v[156:159], v[168:171], v[32:47]
	v_max_f32_e32 v96, v81, v81
	v_max_f32_e32 v97, v80, v80
	v_max_f32_e32 v96, v97, v96
	s_nop 3
	v_max3_f32 v97, v82, v83, v65
	v_max3_f32 v96, v96, v64, v66
	v_max3_f32 v96, v96, v67, v84
	v_max3_f32 v97, v97, v86, v87
	v_max3_f32 v96, v96, v85, v68
	s_waitcnt lgkmcnt(12)
	v_mfma_f32_32x32x16_bf16 v[16:31], v[156:159], v[164:167], v[16:31]
	v_max3_f32 v97, v97, v70, v71
	v_max3_f32 v96, v96, v69, v88
	v_max3_f32 v97, v97, v90, v91
	v_max3_f32 v96, v96, v89, v72
	v_max3_f32 v97, v97, v74, v75
	v_max3_f32 v96, v96, v73, v92
	v_max3_f32 v97, v97, v94, v95
	s_waitcnt lgkmcnt(10)
	v_mfma_f32_32x32x16_bf16 v[32:47], v[152:155], v[160:163], v[32:47]
	v_max3_f32 v96, v96, v93, v76
	v_max3_f32 v97, v97, v78, v79
	v_add_f32_e32 v223, v14, v15
	v_max3_f32 v14, v96, v77, v97
	v_mov_b32_e32 v15, v14
	s_nop 1
	v_permlane32_swap_b32_e32 v14, v15
	s_add_i32 s8, s38, s46
	s_mov_b32 s9, m0
	s_mov_b32 m0, s8
	s_nop 0
	global_load_lds_dwordx4 v[202:203], off
	s_mov_b32 m0, s9
	v_max_f32_e32 v14, v14, v15
	s_add_i32 s8, s13, s47
	s_mov_b32 s9, m0
	s_mov_b32 m0, s8
	s_nop 0
	global_load_lds_dwordx4 v[200:201], off
	s_mov_b32 m0, s9
	v_cmp_lt_f32_e32 vcc, s53, v14
	s_cmp_lg_u64 vcc, 0
	s_cselect_b64 s[8:9], -1, 0
	s_cbranch_vccnz .LBB0_1558
.LBB0_1551:
	v_exp_f32_e32 v80, v80
	v_exp_f32_e32 v81, v81
	v_exp_f32_e32 v82, v82
	v_exp_f32_e32 v83, v83
	v_exp_f32_e32 v84, v84
	v_exp_f32_e32 v85, v85
	v_exp_f32_e32 v86, v86
	v_exp_f32_e32 v87, v87
	v_add_u32_e32 v14, s13, v220
	ds_read_b128 v[188:191], v14
	ds_read_b128 v[184:187], v14 offset:512
	v_exp_f32_e32 v88, v88
	v_exp_f32_e32 v89, v89
	v_exp_f32_e32 v90, v90
	v_exp_f32_e32 v91, v91
	ds_read_b128 v[180:183], v14 offset:2048
	ds_read_b128 v[176:179], v14 offset:2560
	s_waitcnt lgkmcnt(12)
	v_mfma_f32_32x32x16_bf16 v[16:31], v[152:155], v[116:119], v[16:31]
	v_exp_f32_e32 v92, v92
	v_exp_f32_e32 v93, v93
	v_exp_f32_e32 v94, v94
	v_exp_f32_e32 v95, v95
	ds_read_b128 v[172:175], v14 offset:4096
	ds_read_b128 v[168:171], v14 offset:4608
	s_waitcnt lgkmcnt(12)
	v_mfma_f32_32x32x16_bf16 v[32:47], v[144:147], v[112:115], v[32:47]
	v_exp_f32_e32 v64, v64
	v_exp_f32_e32 v65, v65
	v_exp_f32_e32 v66, v66
	v_exp_f32_e32 v67, v67
	ds_read_b128 v[164:167], v14 offset:6144
	ds_read_b128 v[160:163], v14 offset:6656
	s_waitcnt lgkmcnt(12)
	v_mfma_f32_32x32x16_bf16 v[16:31], v[144:147], v[10:13], v[16:31]
	v_exp_f32_e32 v68, v68
	v_exp_f32_e32 v69, v69
	v_exp_f32_e32 v70, v70
	v_exp_f32_e32 v71, v71
	s_waitcnt lgkmcnt(10)
	v_mfma_f32_32x32x16_bf16 v[32:47], v[136:139], v[6:9], v[32:47]
	v_exp_f32_e32 v72, v72
	v_exp_f32_e32 v73, v73
	v_exp_f32_e32 v74, v74
	v_exp_f32_e32 v75, v75
	s_waitcnt lgkmcnt(8)
	v_mfma_f32_32x32x16_bf16 v[16:31], v[136:139], v[2:5], v[16:31]
	v_exp_f32_e32 v76, v76
	v_exp_f32_e32 v77, v77
	v_exp_f32_e32 v78, v78
	v_exp_f32_e32 v79, v79
	s_waitcnt vmcnt(2) lgkmcnt(0)
	s_barrier
	s_andn2_b64 vcc, exec, s[8:9]
	s_cbranch_vccnz .LBB0_1553
	s_waitcnt lgkmcnt(0)
	ds_read_b128 v[2:5], v0 offset:49248
	ds_read_b128 v[6:9], v0 offset:49216
	ds_read_b128 v[10:13], v0 offset:49184
	ds_read_b128 v[96:99], v0 offset:49152
	s_waitcnt lgkmcnt(3)
	v_pk_mul_f32 v[44:45], v[44:45], v[2:3]
	s_waitcnt lgkmcnt(2)
	v_pk_mul_f32 v[40:41], v[40:41], v[6:7]
	s_waitcnt lgkmcnt(1)
	v_pk_mul_f32 v[36:37], v[36:37], v[10:11]
	v_pk_mul_f32 v[46:47], v[46:47], v[4:5]
	v_pk_mul_f32 v[42:43], v[42:43], v[8:9]
	v_pk_mul_f32 v[38:39], v[38:39], v[12:13]
	s_waitcnt lgkmcnt(0)
	v_pk_mul_f32 v[34:35], v[34:35], v[98:99]
	v_pk_mul_f32 v[32:33], v[32:33], v[96:97]
	v_pk_mul_f32 v[28:29], v[28:29], v[2:3]
	v_pk_mul_f32 v[24:25], v[24:25], v[6:7]
	v_pk_mul_f32 v[20:21], v[20:21], v[10:11]
	v_pk_mul_f32 v[30:31], v[30:31], v[4:5]
	v_pk_mul_f32 v[26:27], v[26:27], v[8:9]
	v_pk_mul_f32 v[22:23], v[22:23], v[12:13]
	v_pk_mul_f32 v[18:19], v[18:19], v[98:99]
	v_pk_mul_f32 v[16:17], v[16:17], v[96:97]
